# v46 + kernel-wide static s_setprio 1 for waves 0-3
# speedup vs baseline: 1.0175x; 1.0175x over previous
_Z6mk_fwd4Args:
	s_mov_b64 s[72:73], s[0:1]
	s_load_dword s56, s[0:1], 0x130
	s_add_u32 s0, s72, 0x130
	s_addc_u32 s1, s73, 0
	v_and_b32_e32 v208, 0x3ff, v0
	v_readfirstlane_b32 s98, v208
	s_bitcmp1_b32 s98, 8
	s_cbranch_scc1 .Lsp_entry
	s_setprio 1
